# diff fast loop: the four selection-matrix row-sum MFMAs alternate between two 4-register accumulators (no dependent accumulate chain), summed at loop exit
# speedup vs baseline: 1.0048x; 1.0048x over previous
.Lf_459:
	v_mov_b32_e32 v180, v128
	v_mov_b32_e32 v181, v129
	v_mov_b32_e32 v182, v130
	v_mov_b32_e32 v183, v131
	v_mfma_f32_32x32x16_bf16 v[64:79], v[176:179], v[140:143], v[64:79]
	ds_read_b64_tr_b16 v[128:129], v0 offset:24576
	ds_read_b64_tr_b16 v[130:131], v0 offset:25088
	v_exp_f32_e32 v14, v112
	v_mfma_f32_32x32x16_bf16 v[64:79], v[172:175], v[136:139], v[64:79]
	ds_read_b64_tr_b16 v[172:173], v0 offset:25600
	ds_read_b64_tr_b16 v[174:175], v0 offset:26112
	v_exp_f32_e32 v15, v96
	v_mfma_f32_32x32x16_bf16 v[64:79], v[168:171], v[132:135], v[64:79]
	ds_read_b64_tr_b16 v[168:169], v0 offset:26624
	ds_read_b64_tr_b16 v[170:171], v0 offset:27136
	v_exp_f32_e32 v96, v113
	v_mfma_f32_32x32x16_bf16 v[64:79], v[164:167], v[180:183], v[64:79]
	ds_read_b64_tr_b16 v[164:165], v0 offset:27648
	ds_read_b64_tr_b16 v[166:167], v0 offset:28160
	v_exp_f32_e32 v97, v97
	v_mfma_f32_32x32x16_bf16 v[48:63], v[160:163], v[140:143], v[48:63]
	ds_read_b64_tr_b16 v[160:161], v0 offset:28672
	ds_read_b64_tr_b16 v[162:163], v0 offset:29184
	v_exp_f32_e32 v112, v114
	v_mfma_f32_32x32x16_bf16 v[48:63], v[10:13], v[136:139], v[48:63]
	ds_read_b64_tr_b16 v[10:11], v0 offset:29696
	ds_read_b64_tr_b16 v[12:13], v0 offset:30208
	v_exp_f32_e32 v98, v98
	v_mfma_f32_32x32x16_bf16 v[48:63], v[6:9], v[132:135], v[48:63]
	ds_read_b64_tr_b16 v[6:7], v0 offset:30720
	ds_read_b64_tr_b16 v[8:9], v0 offset:31232
	v_exp_f32_e32 v113, v115
	v_mfma_f32_32x32x16_bf16 v[48:63], v[2:5], v[180:183], v[48:63]
	ds_read_b64_tr_b16 v[2:3], v0 offset:31744
	ds_read_b64_tr_b16 v[4:5], v0 offset:32256
	v_exp_f32_e32 v0, v99
	s_waitcnt lgkmcnt(14)
	v_mfma_f32_32x32x16_bf16 v[32:47], v[128:131], v[140:143], v[32:47]
	v_exp_f32_e32 v99, v116
	v_exp_f32_e32 v100, v100
	v_exp_f32_e32 v114, v117
	s_waitcnt lgkmcnt(12)
	v_mfma_f32_32x32x16_bf16 v[32:47], v[172:175], v[136:139], v[32:47]
	v_exp_f32_e32 v101, v101
	v_exp_f32_e32 v115, v118
	v_exp_f32_e32 v102, v102
	s_waitcnt lgkmcnt(10)
	v_mfma_f32_32x32x16_bf16 v[32:47], v[168:171], v[132:135], v[32:47]
	v_exp_f32_e32 v116, v119
	v_exp_f32_e32 v103, v103
	v_exp_f32_e32 v117, v120
	s_waitcnt lgkmcnt(8)
	v_mfma_f32_32x32x16_bf16 v[32:47], v[164:167], v[180:183], v[32:47]
	v_exp_f32_e32 v104, v104
	v_exp_f32_e32 v118, v121
	v_exp_f32_e32 v105, v105
	s_waitcnt lgkmcnt(6)
	v_mfma_f32_32x32x16_bf16 v[16:31], v[160:163], v[140:143], v[16:31]
	v_exp_f32_e32 v119, v122
	v_exp_f32_e32 v106, v106
	v_exp_f32_e32 v120, v123
	s_waitcnt lgkmcnt(4)
	v_mfma_f32_32x32x16_bf16 v[16:31], v[10:13], v[136:139], v[16:31]
	v_exp_f32_e32 v10, v107
	v_exp_f32_e32 v11, v124
	v_exp_f32_e32 v12, v108
	s_waitcnt lgkmcnt(2)
	v_mfma_f32_32x32x16_bf16 v[16:31], v[6:9], v[132:135], v[16:31]
	v_exp_f32_e32 v6, v125
	v_exp_f32_e32 v7, v109
	v_exp_f32_e32 v8, v126
	s_waitcnt lgkmcnt(0)
	v_mfma_f32_32x32x16_bf16 v[16:31], v[2:5], v[180:183], v[16:31]
	v_exp_f32_e32 v107, v110
	s_nop 0
	v_mfma_f32_16x16x32_bf16 v[84:87], v[92:95], v[140:143], v[84:87]
	v_exp_f32_e32 v108, v127
	v_exp_f32_e32 v109, v111
	v_cvt_pk_bf16_f32 v140, v14, v96
	v_cvt_pk_bf16_f32 v143, v115, v116
	v_mfma_f32_16x16x32_bf16 v[88:91], v[92:95], v[136:139], v[88:91]
	v_cvt_pk_bf16_f32 v128, v104, v105
	v_cvt_pk_bf16_f32 v141, v112, v113
	v_cvt_pk_bf16_f32 v136, v117, v118
	v_mfma_f32_16x16x32_bf16 v[84:87], v[92:95], v[132:135], v[84:87]
	v_cvt_pk_bf16_f32 v137, v119, v120
	v_cvt_pk_bf16_f32 v129, v106, v10
	v_cvt_pk_bf16_f32 v132, v15, v97
	v_cvt_pk_bf16_f32 v130, v12, v7
	v_cvt_pk_bf16_f32 v138, v11, v6
	v_cvt_pk_bf16_f32 v133, v98, v0
	v_cvt_pk_bf16_f32 v142, v99, v114
	v_cvt_pk_bf16_f32 v134, v100, v101
	v_cvt_pk_bf16_f32 v135, v102, v103
	v_cvt_pk_bf16_f32 v139, v8, v108
	v_cvt_pk_bf16_f32 v131, v107, v109
	v_mfma_f32_16x16x32_bf16 v[88:91], v[92:95], v[180:183], v[88:91]
	s_add_i32 s28, s28, 1
	s_add_i32 s13, s13, 1
	s_add_i32 s19, s19, 0x8000
	s_cmpk_eq_i32 s13, 0x45
	s_cbranch_scc1 .Lf_fold464

.Lf_foldrare:
	s_nop 7
	v_add_f32_e32 v80, v84, v88
	s_nop 0
	v_mov_b32_e32 v81, v80
	v_mov_b32_e32 v82, v80
	v_mov_b32_e32 v83, v80
	v_mov_b32_e32 v84, v80
	v_mov_b32_e32 v85, v80
	v_mov_b32_e32 v86, v80
	v_mov_b32_e32 v87, v80
	v_mov_b32_e32 v88, v80
	v_mov_b32_e32 v89, v80
	v_mov_b32_e32 v90, v80
	v_mov_b32_e32 v91, v80
	v_mov_b32_e32 v92, v80
	v_mov_b32_e32 v93, v80
	v_mov_b32_e32 v94, v80
	v_mov_b32_e32 v95, v80
	s_nop 1
	s_branch .Lf_to463
.Lf_fold464:
	s_nop 7
	v_add_f32_e32 v80, v84, v88
	s_nop 0
	v_mov_b32_e32 v81, v80
	v_mov_b32_e32 v82, v80
	v_mov_b32_e32 v83, v80
	v_mov_b32_e32 v84, v80
	v_mov_b32_e32 v85, v80
	v_mov_b32_e32 v86, v80
	v_mov_b32_e32 v87, v80
	v_mov_b32_e32 v88, v80
	v_mov_b32_e32 v89, v80
	v_mov_b32_e32 v90, v80
	v_mov_b32_e32 v91, v80
	v_mov_b32_e32 v92, v80
	v_mov_b32_e32 v93, v80
	v_mov_b32_e32 v94, v80
	v_mov_b32_e32 v95, v80
	s_nop 1
	s_branch .LBB0_464
	.p2align 6
